# P1 wave roles split: 1280 waves stream modulate rows while the other 768 waves do the weight transposes concurrently; plus P0 changes and P3 epilogue
# baseline (speedup 1.0000x reference)
; __device__ __forceinline__ void modulate_rows(const float* x, const float* mods, int ch_shift, bf16_t* h, int gw, int NGW, int lane) {
;     for (int m = gw; m < T; m += NGW) {
;         const float* mp = mods + (size_t)(m / SEQ) * (NMOD * D) + ch_shift * D;
;         const f32x4* xr = (const f32x4*)(x + (size_t)m * D) + lane;
;         u32x2* o8 = (u32x2*)(h + (size_t)m * D) + lane;
; __global__ void __launch_bounds__(512, 2) fwd_megakernel(Args a_by_value) {
;     ...
;     if (ON(1)) modulate_rows(a->x, mods, 0, H, gw, NGW, lane);
;     if (ON(1)) {
.LBB0_55:
	s_or_b64 exec, exec, s[6:7]
	s_mov_b64 s[6:7], s[0:1]
	s_barrier
	s_load_dwordx2 s[10:11], s[6:7], 0xb8
	s_cmp_lt_i32 s30, 0x8000
	s_cselect_b64 s[16:17], -1, 0
	s_mov_b32 s98, s30
	s_mov_b32 s99, s34
	s_cmp_gt_i32 s34, 0x500
	s_cbranch_scc0 .Lp1_nosplit
	s_movk_i32 s34, 0x500
	s_cmp_lt_i32 s98, 0x500
	s_cbranch_scc1 .Lp1_nosplit
	s_mov_b32 s30, 0x8000
.Lp1_nosplit:
	s_cmpk_gt_i32 s30, 0x7fff
	v_or_b32_e32 v160, 64, v156
	v_lshlrev_b32_e32 v152, 4, v156
	s_cbranch_scc1 .LBB0_58
	s_load_dwordx2 s[12:13], s[6:7], 0x0
	s_ashr_i32 s31, s30, 31
	s_lshl_b64 s[14:15], s[30:31], 13
	v_mov_b32_e32 v153, 0
	v_mov_b32_e32 v159, v153
	s_waitcnt lgkmcnt(0)
	s_add_u32 s12, s12, s14
	s_addc_u32 s13, s13, s15
	v_lshl_add_u64 v[0:1], s[12:13], 0, v[152:153]
	s_mov_b64 s[12:13], 0x1000
	s_ashr_i32 s35, s34, 31
	v_lshl_add_u64 v[0:1], v[0:1], 0, s[12:13]
	s_lshl_b64 s[12:13], s[34:35], 13
	s_lshl_b64 s[14:15], s[30:31], 12
	s_add_u32 s14, s10, s14
	s_addc_u32 s15, s11, s15
	v_or_b32_e32 v6, 0x80, v156
	v_or_b32_e32 v8, 0xc0, v156
	v_or_b32_e32 v10, 0x100, v156
	v_or_b32_e32 v12, 0x140, v156
	v_or_b32_e32 v14, 0x180, v156
	v_or_b32_e32 v16, 0x1c0, v156
	v_lshl_add_u64 v[2:3], s[14:15], 0, v[158:159]
	s_mov_b64 s[14:15], 0xba00000
	v_lshl_add_u64 v[2:3], v[2:3], 0, s[14:15]
	s_lshl_b64 s[14:15], s[34:35], 12
	v_lshlrev_b32_e32 v4, 4, v156
	v_lshlrev_b32_e32 v5, 4, v160
	v_lshlrev_b32_e32 v6, 4, v6
	v_lshlrev_b32_e32 v7, 4, v8
	v_lshlrev_b32_e32 v8, 4, v10
	v_lshlrev_b32_e32 v9, 4, v12
	v_lshlrev_b32_e32 v10, 4, v14
	v_lshlrev_b32_e32 v11, 4, v16
	s_mov_b32 s22, s30

; __global__ void __launch_bounds__(512, 2) fwd_megakernel(Args a_by_value) {
;     ...
;     if (ON(1)) {
;         constexpr int total = (FF / 64) * (D / 32) + (D / 64) * ((6144 + 32) / 32);
;         for (int it = gw; it < total; it += NGW) {
;             int r = it;
;             if (tj(a->w_d1, FF, D, Wd, 0, D, 0, 0, r, scr, lane)) continue;
;             tj(a->w_in, D, WIN_SRC, Win, WR_GLA, 6144 + 32, 0, 0, r, scr, lane);
;         }
.LBB0_58:
	s_cmp_gt_i32 s99, 0x500
	s_cbranch_scc0 .Lp1_t_go
	s_sub_i32 s30, s98, 0x500
	s_sub_i32 s34, s99, 0x500
	s_cmp_lt_i32 s30, 0
	s_cbranch_scc1 .LBB0_71

; __device__ __forceinline__ void grid_barrier(unsigned* bar, unsigned& gen, unsigned G) {
;     asm volatile("s_waitcnt vmcnt(0) lgkmcnt(0)" ::: "memory");
;     __syncthreads();
;     ++gen;
;     if (threadIdx.x == 0) {
;         __builtin_amdgcn_fence(__ATOMIC_RELEASE, "agent");
;         asm volatile("s_waitcnt vmcnt(0)" ::: "memory");
;         if ((G & 7u) == 0u) {
;             const unsigned x = blockIdx.x & 7u, per = G >> 3;
;             unsigned* cnt1 = bar + 64 * (1 + x); unsigned* cnt2 = bar + 64 * 9; unsigned* rel = bar + 64 * (10 + x);
;             const unsigned old = __hip_atomic_fetch_add(cnt1, 1u, __ATOMIC_RELAXED, __HIP_MEMORY_SCOPE_AGENT);
.LBB0_71:
	s_mov_b32 s30, s98
	s_mov_b32 s34, s99
	s_waitcnt lgkmcnt(0)
	s_mov_b64 s[10:11], s[0:1]
	s_waitcnt vmcnt(0) lgkmcnt(0)
	s_barrier
	s_and_saveexec_b64 s[6:7], s[4:5]
	s_cbranch_execz .LBB0_94
	s_load_dwordx2 s[10:11], s[10:11], 0xb8
	buffer_wbl2 sc1
	s_waitcnt vmcnt(0) lgkmcnt(0)
	s_waitcnt vmcnt(0)
	s_add_u32 s12, s10, 0x80000
	s_addc_u32 s13, s11, 0
	s_and_b32 s14, s40, 7
	s_cmp_lg_u32 s14, 0
	s_cbranch_scc0 .LBB0_78
	s_mov_b64 s[18:19], exec
	v_mbcnt_lo_u32_b32 v0, s18, 0
	v_mbcnt_hi_u32_b32 v0, s19, v0
	v_cmp_eq_u32_e32 vcc, 0, v0
	s_and_saveexec_b64 s[14:15], vcc
	s_cbranch_execz .LBB0_75
	s_bcnt1_i32_b64 s18, s[18:19]
	v_mov_b32_e32 v0, 0
	v_mov_b32_e32 v1, s18
	global_atomic_add v0, v1, s[12:13]
